# SwiGLU GEMM epilogues rewritten with packed f32 mul/add (v_pk_mul_f32 / v_pk_add_f32 with SGPR-pair constants), 26 percent fewer VALU instructions, same arithmetic order; rest as previous best
# baseline (speedup 1.0000x reference)
; __device__ __forceinline__ unsigned cvt_pk_bf16(float lo, float hi) { const f32x2_cv v = {lo, hi}; return __builtin_bit_cast(unsigned, __builtin_convertvector(v, bf16x2_cv)); }
; __device__ __forceinline__ float siluf_(float x) { return x * sigmoidf_(x); }
;     __device__ __forceinline__ void operator()(const f32x4 (&acc)[2][2][4][2], const Unit& u, int wr, int wc, int fr, int fq) const {
;         const int row0 = u.pm * BM + wr * 64 + fr, col0 = u.pn * HALF + wc * 32 + 8 * fq;
; #pragma unroll
;         for (int ai = 0; ai < 2; ++ai)
; #pragma unroll
;             for (int m = 0; m < 4; ++m) { bf16_t* rowp = O + (size_t)(row0 + ai * HALF + m * 16) * ldc + col0;
;                 const f32x4 g0 = acc[ai][0][m][0], g1 = acc[ai][0][m][1], u0 = acc[ai][1][m][0], u1 = acc[ai][1][m][1];
;                 u32x4 w; w.x = cvt_pk_bf16(siluf_(g0[0]) * u0[0], siluf_(g0[1]) * u0[1]); w.y = cvt_pk_bf16(siluf_(g0[2]) * u0[2], siluf_(g0[3]) * u0[3]);
;                 w.z = cvt_pk_bf16(siluf_(g1[0]) * u1[0], siluf_(g1[1]) * u1[1]); w.w = cvt_pk_bf16(siluf_(g1[2]) * u1[2], siluf_(g1[3]) * u1[3]);
;                 __builtin_nontemporal_store(w, (u32x4*)rowp); }
.LBB0_51:
	s_mov_b32 s98, 0xbfb8aa3b
	s_mov_b32 s99, 0xbfb8aa3b
	s_mov_b32 s100, 1.0
	s_mov_b32 s101, 1.0
	v_lshl_add_u32 v156, s18, 8, v150
	v_lshl_or_b32 v146, s44, 7, v152
	v_ashrrev_i32_e32 v147, 31, v146
	v_mov_b64_e32 v[148:149], s[68:69]
	v_lshlrev_b64 v[146:147], 1, v[146:147]
	v_mov_b32_e32 v216, v156
	v_mad_i64_i32 v[216:217], s[20:21], v216, s43, v[148:149]
	v_add_u32_e32 v218, 0x10, v156
	v_mad_i64_i32 v[218:219], s[20:21], v218, s43, v[148:149]
	v_add_u32_e32 v220, 0x20, v156
	v_mad_i64_i32 v[220:221], s[20:21], v220, s43, v[148:149]
	v_add_u32_e32 v222, 0x30, v156
	v_mad_i64_i32 v[222:223], s[20:21], v222, s43, v[148:149]
	v_add_u32_e32 v224, 0x80, v156
	v_mad_i64_i32 v[224:225], s[20:21], v224, s43, v[148:149]
	v_add_u32_e32 v226, 0x90, v156
	v_mad_i64_i32 v[226:227], s[20:21], v226, s43, v[148:149]
	v_add_u32_e32 v228, 0xa0, v156
	v_mad_i64_i32 v[228:229], s[20:21], v228, s43, v[148:149]
	v_add_u32_e32 v230, 0xb0, v156
	v_mad_i64_i32 v[230:231], s[20:21], v230, s43, v[148:149]
	v_lshl_add_u64 v[216:217], v[216:217], 0, v[146:147]
	v_lshl_add_u64 v[218:219], v[218:219], 0, v[146:147]
	v_lshl_add_u64 v[220:221], v[220:221], 0, v[146:147]
	v_lshl_add_u64 v[222:223], v[222:223], 0, v[146:147]
	v_lshl_add_u64 v[224:225], v[224:225], 0, v[146:147]
	v_lshl_add_u64 v[226:227], v[226:227], 0, v[146:147]
	v_lshl_add_u64 v[228:229], v[228:229], 0, v[146:147]
	v_lshl_add_u64 v[230:231], v[230:231], 0, v[146:147]
	v_pk_mul_f32 v[160:161], v[124:125], s[98:99]
	v_pk_mul_f32 v[162:163], v[126:127], s[98:99]
	v_exp_f32_e32 v160, v160
	v_exp_f32_e32 v161, v161
	v_exp_f32_e32 v162, v162
	v_exp_f32_e32 v163, v163
	v_pk_add_f32 v[160:161], v[160:161], s[100:101]
	v_pk_add_f32 v[162:163], v[162:163], s[100:101]
	v_rcp_f32_e32 v160, v160
	v_rcp_f32_e32 v161, v161
	v_rcp_f32_e32 v162, v162
	v_rcp_f32_e32 v163, v163
	v_pk_mul_f32 v[124:125], v[124:125], v[160:161]
	v_pk_mul_f32 v[126:127], v[126:127], v[162:163]
	v_pk_mul_f32 v[120:121], v[124:125], v[120:121]
	v_pk_mul_f32 v[122:123], v[126:127], v[122:123]
	v_cvt_pk_bf16_f32 v120, v120, v121
	v_cvt_pk_bf16_f32 v121, v122, v123
	v_pk_mul_f32 v[160:161], v[116:117], s[98:99]
	v_pk_mul_f32 v[162:163], v[118:119], s[98:99]
	v_exp_f32_e32 v160, v160
	v_exp_f32_e32 v161, v161
	v_exp_f32_e32 v162, v162
	v_exp_f32_e32 v163, v163
	v_pk_add_f32 v[160:161], v[160:161], s[100:101]
	v_pk_add_f32 v[162:163], v[162:163], s[100:101]
	v_rcp_f32_e32 v160, v160
	v_rcp_f32_e32 v161, v161
	v_rcp_f32_e32 v162, v162
	v_rcp_f32_e32 v163, v163
	v_pk_mul_f32 v[116:117], v[116:117], v[160:161]
	v_pk_mul_f32 v[118:119], v[118:119], v[162:163]
	v_pk_mul_f32 v[112:113], v[116:117], v[112:113]
	v_pk_mul_f32 v[114:115], v[118:119], v[114:115]
	v_cvt_pk_bf16_f32 v122, v112, v113
	v_cvt_pk_bf16_f32 v123, v114, v115
	v_pk_mul_f32 v[160:161], v[108:109], s[98:99]
	v_pk_mul_f32 v[162:163], v[110:111], s[98:99]
	v_exp_f32_e32 v160, v160
	v_exp_f32_e32 v161, v161
	v_exp_f32_e32 v162, v162
	v_exp_f32_e32 v163, v163
	v_pk_add_f32 v[160:161], v[160:161], s[100:101]
	v_pk_add_f32 v[162:163], v[162:163], s[100:101]
	v_rcp_f32_e32 v160, v160
	v_rcp_f32_e32 v161, v161
	v_rcp_f32_e32 v162, v162
	v_rcp_f32_e32 v163, v163
	v_pk_mul_f32 v[108:109], v[108:109], v[160:161]
	v_pk_mul_f32 v[110:111], v[110:111], v[162:163]
	v_pk_mul_f32 v[104:105], v[108:109], v[104:105]
	v_pk_mul_f32 v[106:107], v[110:111], v[106:107]
	v_cvt_pk_bf16_f32 v104, v104, v105
	v_cvt_pk_bf16_f32 v105, v106, v107
	v_pk_mul_f32 v[160:161], v[100:101], s[98:99]
	v_pk_mul_f32 v[162:163], v[102:103], s[98:99]
	v_exp_f32_e32 v160, v160
	v_exp_f32_e32 v161, v161
	v_exp_f32_e32 v162, v162
	v_exp_f32_e32 v163, v163
	v_pk_add_f32 v[160:161], v[160:161], s[100:101]
	v_pk_add_f32 v[162:163], v[162:163], s[100:101]
	v_rcp_f32_e32 v160, v160
	v_rcp_f32_e32 v161, v161
	v_rcp_f32_e32 v162, v162
	v_rcp_f32_e32 v163, v163
	v_pk_mul_f32 v[100:101], v[100:101], v[160:161]
	v_pk_mul_f32 v[102:103], v[102:103], v[162:163]
	v_pk_mul_f32 v[96:97], v[100:101], v[96:97]
	v_pk_mul_f32 v[98:99], v[102:103], v[98:99]
	v_cvt_pk_bf16_f32 v106, v96, v97
	v_cvt_pk_bf16_f32 v107, v98, v99
	v_pk_mul_f32 v[160:161], v[92:93], s[98:99]
	v_pk_mul_f32 v[162:163], v[94:95], s[98:99]
	v_exp_f32_e32 v160, v160
	v_exp_f32_e32 v161, v161
	v_exp_f32_e32 v162, v162
	v_exp_f32_e32 v163, v163
	v_pk_add_f32 v[160:161], v[160:161], s[100:101]
	v_pk_add_f32 v[162:163], v[162:163], s[100:101]
	v_rcp_f32_e32 v160, v160
	v_rcp_f32_e32 v161, v161
	v_rcp_f32_e32 v162, v162
	v_rcp_f32_e32 v163, v163
	v_pk_mul_f32 v[92:93], v[92:93], v[160:161]
	v_pk_mul_f32 v[94:95], v[94:95], v[162:163]
	v_pk_mul_f32 v[88:89], v[92:93], v[88:89]
	v_pk_mul_f32 v[90:91], v[94:95], v[90:91]
	v_cvt_pk_bf16_f32 v88, v88, v89
	v_cvt_pk_bf16_f32 v89, v90, v91
	v_pk_mul_f32 v[160:161], v[84:85], s[98:99]
	v_pk_mul_f32 v[162:163], v[86:87], s[98:99]
	v_exp_f32_e32 v160, v160
	v_exp_f32_e32 v161, v161
	v_exp_f32_e32 v162, v162
	v_exp_f32_e32 v163, v163
	v_pk_add_f32 v[160:161], v[160:161], s[100:101]
	v_pk_add_f32 v[162:163], v[162:163], s[100:101]
	v_rcp_f32_e32 v160, v160
	v_rcp_f32_e32 v161, v161
	v_rcp_f32_e32 v162, v162
	v_rcp_f32_e32 v163, v163
	v_pk_mul_f32 v[84:85], v[84:85], v[160:161]
	v_pk_mul_f32 v[86:87], v[86:87], v[162:163]
	v_pk_mul_f32 v[80:81], v[84:85], v[80:81]
	v_pk_mul_f32 v[82:83], v[86:87], v[82:83]
	v_cvt_pk_bf16_f32 v90, v80, v81
	v_cvt_pk_bf16_f32 v91, v82, v83
	v_pk_mul_f32 v[160:161], v[76:77], s[98:99]
	v_pk_mul_f32 v[162:163], v[78:79], s[98:99]
	v_exp_f32_e32 v160, v160
	v_exp_f32_e32 v161, v161
	v_exp_f32_e32 v162, v162
	v_exp_f32_e32 v163, v163
	v_pk_add_f32 v[160:161], v[160:161], s[100:101]
; __device__ __forceinline__ unsigned cvt_pk_bf16(float lo, float hi) { const f32x2_cv v = {lo, hi}; return __builtin_bit_cast(unsigned, __builtin_convertvector(v, bf16x2_cv)); }
; __device__ __forceinline__ float siluf_(float x) { return x * sigmoidf_(x); }
;     __device__ __forceinline__ void operator()(const f32x4 (&acc)[2][2][4][2], const Unit& u, int wr, int wc, int fr, int fq) const {
;     ...
;             for (int m = 0; m < 4; ++m) { bf16_t* rowp = O + (size_t)(row0 + ai * HALF + m * 16) * ldc + col0;
;                 const f32x4 g0 = acc[ai][0][m][0], g1 = acc[ai][0][m][1], u0 = acc[ai][1][m][0], u1 = acc[ai][1][m][1];
;                 u32x4 w; w.x = cvt_pk_bf16(siluf_(g0[0]) * u0[0], siluf_(g0[1]) * u0[1]); w.y = cvt_pk_bf16(siluf_(g0[2]) * u0[2], siluf_(g0[3]) * u0[3]);
;                 w.z = cvt_pk_bf16(siluf_(g1[0]) * u1[0], siluf_(g1[1]) * u1[1]); w.w = cvt_pk_bf16(siluf_(g1[2]) * u1[2], siluf_(g1[3]) * u1[3]);
;                 __builtin_nontemporal_store(w, (u32x4*)rowp); }
; template <class Epi, class Sched, bool ALIGN_EPI = false, bool SP2 = false>
; __device__ __forceinline__ void gemm_phase(PG8_LAS unsigned char* lds, const Gemm g, const Sched& S, const Epi& E) {
;     ...
;         if (!has_next) break;
	v_pk_add_f32 v[162:163], v[162:163], s[100:101]
	v_rcp_f32_e32 v160, v160
	v_rcp_f32_e32 v161, v161
	v_rcp_f32_e32 v162, v162
	v_rcp_f32_e32 v163, v163
	v_pk_mul_f32 v[76:77], v[76:77], v[160:161]
	v_pk_mul_f32 v[78:79], v[78:79], v[162:163]
	v_pk_mul_f32 v[72:73], v[76:77], v[72:73]
	v_pk_mul_f32 v[74:75], v[78:79], v[74:75]
	v_cvt_pk_bf16_f32 v72, v72, v73
	v_cvt_pk_bf16_f32 v73, v74, v75
	v_pk_mul_f32 v[160:161], v[68:69], s[98:99]
	v_pk_mul_f32 v[162:163], v[70:71], s[98:99]
	v_exp_f32_e32 v160, v160
	v_exp_f32_e32 v161, v161
	v_exp_f32_e32 v162, v162
	v_exp_f32_e32 v163, v163
	v_pk_add_f32 v[160:161], v[160:161], s[100:101]
	v_pk_add_f32 v[162:163], v[162:163], s[100:101]
	v_rcp_f32_e32 v160, v160
	v_rcp_f32_e32 v161, v161
	v_rcp_f32_e32 v162, v162
	v_rcp_f32_e32 v163, v163
	v_pk_mul_f32 v[68:69], v[68:69], v[160:161]
	v_pk_mul_f32 v[70:71], v[70:71], v[162:163]
	v_pk_mul_f32 v[64:65], v[68:69], v[64:65]
	v_pk_mul_f32 v[66:67], v[70:71], v[66:67]
	v_cvt_pk_bf16_f32 v74, v64, v65
	v_cvt_pk_bf16_f32 v75, v66, v67
	v_pk_mul_f32 v[160:161], v[60:61], s[98:99]
	v_pk_mul_f32 v[162:163], v[62:63], s[98:99]
	v_exp_f32_e32 v160, v160
	v_exp_f32_e32 v161, v161
	v_exp_f32_e32 v162, v162
	v_exp_f32_e32 v163, v163
	v_pk_add_f32 v[160:161], v[160:161], s[100:101]
	v_pk_add_f32 v[162:163], v[162:163], s[100:101]
	v_rcp_f32_e32 v160, v160
	v_rcp_f32_e32 v161, v161
	v_rcp_f32_e32 v162, v162
	v_rcp_f32_e32 v163, v163
	v_pk_mul_f32 v[60:61], v[60:61], v[160:161]
	v_pk_mul_f32 v[62:63], v[62:63], v[162:163]
	v_pk_mul_f32 v[56:57], v[60:61], v[56:57]
	v_pk_mul_f32 v[58:59], v[62:63], v[58:59]
	v_cvt_pk_bf16_f32 v56, v56, v57
	v_cvt_pk_bf16_f32 v57, v58, v59
	v_pk_mul_f32 v[160:161], v[52:53], s[98:99]
	v_pk_mul_f32 v[162:163], v[54:55], s[98:99]
	v_exp_f32_e32 v160, v160
	v_exp_f32_e32 v161, v161
	v_exp_f32_e32 v162, v162
	v_exp_f32_e32 v163, v163
	v_pk_add_f32 v[160:161], v[160:161], s[100:101]
	v_pk_add_f32 v[162:163], v[162:163], s[100:101]
	v_rcp_f32_e32 v160, v160
	v_rcp_f32_e32 v161, v161
	v_rcp_f32_e32 v162, v162
	v_rcp_f32_e32 v163, v163
	v_pk_mul_f32 v[52:53], v[52:53], v[160:161]
	v_pk_mul_f32 v[54:55], v[54:55], v[162:163]
	v_pk_mul_f32 v[48:49], v[52:53], v[48:49]
	v_pk_mul_f32 v[50:51], v[54:55], v[50:51]
	v_cvt_pk_bf16_f32 v58, v48, v49
	v_cvt_pk_bf16_f32 v59, v50, v51
	v_pk_mul_f32 v[160:161], v[44:45], s[98:99]
	v_pk_mul_f32 v[162:163], v[46:47], s[98:99]
	v_exp_f32_e32 v160, v160
	v_exp_f32_e32 v161, v161
	v_exp_f32_e32 v162, v162
	v_exp_f32_e32 v163, v163
	v_pk_add_f32 v[160:161], v[160:161], s[100:101]
	v_pk_add_f32 v[162:163], v[162:163], s[100:101]
	v_rcp_f32_e32 v160, v160
	v_rcp_f32_e32 v161, v161
	v_rcp_f32_e32 v162, v162
	v_rcp_f32_e32 v163, v163
	v_pk_mul_f32 v[44:45], v[44:45], v[160:161]
	v_pk_mul_f32 v[46:47], v[46:47], v[162:163]
	v_pk_mul_f32 v[40:41], v[44:45], v[40:41]
	v_pk_mul_f32 v[42:43], v[46:47], v[42:43]
	v_cvt_pk_bf16_f32 v40, v40, v41
	v_cvt_pk_bf16_f32 v41, v42, v43
	v_pk_mul_f32 v[160:161], v[36:37], s[98:99]
	v_pk_mul_f32 v[162:163], v[38:39], s[98:99]
	v_exp_f32_e32 v160, v160
	v_exp_f32_e32 v161, v161
	v_exp_f32_e32 v162, v162
	v_exp_f32_e32 v163, v163
	v_pk_add_f32 v[160:161], v[160:161], s[100:101]
	v_pk_add_f32 v[162:163], v[162:163], s[100:101]
	v_rcp_f32_e32 v160, v160
	v_rcp_f32_e32 v161, v161
	v_rcp_f32_e32 v162, v162
	v_rcp_f32_e32 v163, v163
	v_pk_mul_f32 v[36:37], v[36:37], v[160:161]
	v_pk_mul_f32 v[38:39], v[38:39], v[162:163]
	v_pk_mul_f32 v[32:33], v[36:37], v[32:33]
	v_pk_mul_f32 v[34:35], v[38:39], v[34:35]
	v_cvt_pk_bf16_f32 v42, v32, v33
	v_cvt_pk_bf16_f32 v43, v34, v35
	v_pk_mul_f32 v[160:161], v[28:29], s[98:99]
	v_pk_mul_f32 v[162:163], v[30:31], s[98:99]
	v_exp_f32_e32 v160, v160
	v_exp_f32_e32 v161, v161
	v_exp_f32_e32 v162, v162
	v_exp_f32_e32 v163, v163
	v_pk_add_f32 v[160:161], v[160:161], s[100:101]
	v_pk_add_f32 v[162:163], v[162:163], s[100:101]
	v_rcp_f32_e32 v160, v160
	v_rcp_f32_e32 v161, v161
	v_rcp_f32_e32 v162, v162
	v_rcp_f32_e32 v163, v163
	v_pk_mul_f32 v[28:29], v[28:29], v[160:161]
	v_pk_mul_f32 v[30:31], v[30:31], v[162:163]
	v_pk_mul_f32 v[24:25], v[28:29], v[24:25]
	v_pk_mul_f32 v[26:27], v[30:31], v[26:27]
	v_cvt_pk_bf16_f32 v24, v24, v25
	v_cvt_pk_bf16_f32 v25, v26, v27
	v_pk_mul_f32 v[160:161], v[20:21], s[98:99]
	v_pk_mul_f32 v[162:163], v[22:23], s[98:99]
	v_exp_f32_e32 v160, v160
	v_exp_f32_e32 v161, v161
	v_exp_f32_e32 v162, v162
	v_exp_f32_e32 v163, v163
	v_pk_add_f32 v[160:161], v[160:161], s[100:101]
	v_pk_add_f32 v[162:163], v[162:163], s[100:101]
	v_rcp_f32_e32 v160, v160
	v_rcp_f32_e32 v161, v161
	v_rcp_f32_e32 v162, v162
	v_rcp_f32_e32 v163, v163
	v_pk_mul_f32 v[20:21], v[20:21], v[160:161]
	v_pk_mul_f32 v[22:23], v[22:23], v[162:163]
	v_pk_mul_f32 v[16:17], v[20:21], v[16:17]
	v_pk_mul_f32 v[18:19], v[22:23], v[18:19]
	v_cvt_pk_bf16_f32 v26, v16, v17
	v_cvt_pk_bf16_f32 v27, v18, v19
	v_pk_mul_f32 v[160:161], v[12:13], s[98:99]
	v_pk_mul_f32 v[162:163], v[14:15], s[98:99]
	v_exp_f32_e32 v160, v160
	v_exp_f32_e32 v161, v161
	v_exp_f32_e32 v162, v162
	v_exp_f32_e32 v163, v163
	v_pk_add_f32 v[160:161], v[160:161], s[100:101]
	v_pk_add_f32 v[162:163], v[162:163], s[100:101]
	v_rcp_f32_e32 v160, v160
	v_rcp_f32_e32 v161, v161
	v_rcp_f32_e32 v162, v162
	v_rcp_f32_e32 v163, v163
	v_pk_mul_f32 v[12:13], v[12:13], v[160:161]
	v_pk_mul_f32 v[14:15], v[14:15], v[162:163]
	v_pk_mul_f32 v[8:9], v[12:13], v[8:9]
	v_pk_mul_f32 v[10:11], v[14:15], v[10:11]
	v_cvt_pk_bf16_f32 v8, v8, v9
	v_cvt_pk_bf16_f32 v9, v10, v11
	v_pk_mul_f32 v[160:161], v[4:5], s[98:99]
	v_pk_mul_f32 v[162:163], v[6:7], s[98:99]
	v_exp_f32_e32 v160, v160
	v_exp_f32_e32 v161, v161
	v_exp_f32_e32 v162, v162
	v_exp_f32_e32 v163, v163
	v_pk_add_f32 v[160:161], v[160:161], s[100:101]
	v_pk_add_f32 v[162:163], v[162:163], s[100:101]
	v_rcp_f32_e32 v160, v160
	v_rcp_f32_e32 v161, v161
	v_rcp_f32_e32 v162, v162
	v_rcp_f32_e32 v163, v163
	v_pk_mul_f32 v[4:5], v[4:5], v[160:161]
	v_pk_mul_f32 v[6:7], v[6:7], v[162:163]
	v_pk_mul_f32 v[0:1], v[4:5], v[0:1]
	v_pk_mul_f32 v[2:3], v[6:7], v[2:3]
	v_cvt_pk_bf16_f32 v10, v0, v1
	v_cvt_pk_bf16_f32 v11, v2, v3
	s_andn2_b64 vcc, exec, s[6:7]
	s_mov_b64 s[6:7], -1
	global_store_dwordx4 v[216:217], v[120:123], off nt
	global_store_dwordx4 v[218:219], v[104:107], off nt
	global_store_dwordx4 v[220:221], v[88:91], off nt
	global_store_dwordx4 v[222:223], v[72:75], off nt
	global_store_dwordx4 v[224:225], v[56:59], off nt
	global_store_dwordx4 v[226:227], v[40:43], off nt
	global_store_dwordx4 v[228:229], v[24:27], off nt
	global_store_dwordx4 v[230:231], v[8:11], off nt
	s_cbranch_vccnz .LBB0_44
	s_andn2_b64 vcc, exec, s[2:3]
	s_cbranch_vccnz .LBB0_43
	s_barrier
	s_branch .LBB0_43

; __device__ __forceinline__ unsigned cvt_pk_bf16(float lo, float hi) { const f32x2_cv v = {lo, hi}; return __builtin_bit_cast(unsigned, __builtin_convertvector(v, bf16x2_cv)); }
; __device__ __forceinline__ float siluf_(float x) { return x * sigmoidf_(x); }
;     __device__ __forceinline__ void operator()(const f32x4 (&acc)[2][2][4][2], const Unit& u, int wr, int wc, int fr, int fq) const {
;         const int row0 = u.pm * BM + wr * 64 + fr, col0 = u.pn * HALF + wc * 32 + 8 * fq;
; #pragma unroll
;         for (int ai = 0; ai < 2; ++ai)
; #pragma unroll
;             for (int m = 0; m < 4; ++m) { bf16_t* rowp = O + (size_t)(row0 + ai * HALF + m * 16) * ldc + col0;
;                 const f32x4 g0 = acc[ai][0][m][0], g1 = acc[ai][0][m][1], u0 = acc[ai][1][m][0], u1 = acc[ai][1][m][1];
;                 u32x4 w; w.x = cvt_pk_bf16(siluf_(g0[0]) * u0[0], siluf_(g0[1]) * u0[1]); w.y = cvt_pk_bf16(siluf_(g0[2]) * u0[2], siluf_(g0[3]) * u0[3]);
;                 w.z = cvt_pk_bf16(siluf_(g1[0]) * u1[0], siluf_(g1[1]) * u1[1]); w.w = cvt_pk_bf16(siluf_(g1[2]) * u1[2], siluf_(g1[3]) * u1[3]);
;                 __builtin_nontemporal_store(w, (u32x4*)rowp); }
.LBB0_969:
	s_mov_b32 s98, 0xbfb8aa3b
	s_mov_b32 s99, 0xbfb8aa3b
	s_mov_b32 s100, 1.0
	s_mov_b32 s101, 1.0
	v_lshl_add_u32 v156, s20, 8, v150
	v_lshl_or_b32 v146, s44, 7, v152
	v_ashrrev_i32_e32 v147, 31, v146
	v_mov_b64_e32 v[148:149], s[68:69]
	v_lshlrev_b64 v[146:147], 1, v[146:147]
	v_mov_b32_e32 v216, v156
	v_mad_i64_i32 v[216:217], s[22:23], v216, s43, v[148:149]
	v_add_u32_e32 v218, 0x10, v156
	v_mad_i64_i32 v[218:219], s[22:23], v218, s43, v[148:149]
	v_add_u32_e32 v220, 0x20, v156
	v_mad_i64_i32 v[220:221], s[22:23], v220, s43, v[148:149]
	v_add_u32_e32 v222, 0x30, v156
	v_mad_i64_i32 v[222:223], s[22:23], v222, s43, v[148:149]
	v_add_u32_e32 v224, 0x80, v156
	v_mad_i64_i32 v[224:225], s[22:23], v224, s43, v[148:149]
	v_add_u32_e32 v226, 0x90, v156
	v_mad_i64_i32 v[226:227], s[22:23], v226, s43, v[148:149]
	v_add_u32_e32 v228, 0xa0, v156
	v_mad_i64_i32 v[228:229], s[22:23], v228, s43, v[148:149]
	v_add_u32_e32 v230, 0xb0, v156
	v_mad_i64_i32 v[230:231], s[22:23], v230, s43, v[148:149]
	v_lshl_add_u64 v[216:217], v[216:217], 0, v[146:147]
	v_lshl_add_u64 v[218:219], v[218:219], 0, v[146:147]
	v_lshl_add_u64 v[220:221], v[220:221], 0, v[146:147]
	v_lshl_add_u64 v[222:223], v[222:223], 0, v[146:147]
	v_lshl_add_u64 v[224:225], v[224:225], 0, v[146:147]
	v_lshl_add_u64 v[226:227], v[226:227], 0, v[146:147]
	v_lshl_add_u64 v[228:229], v[228:229], 0, v[146:147]
	v_lshl_add_u64 v[230:231], v[230:231], 0, v[146:147]
	v_pk_mul_f32 v[160:161], v[124:125], s[98:99]
	v_pk_mul_f32 v[162:163], v[126:127], s[98:99]
	v_exp_f32_e32 v160, v160
	v_exp_f32_e32 v161, v161
	v_exp_f32_e32 v162, v162
	v_exp_f32_e32 v163, v163
	v_pk_add_f32 v[160:161], v[160:161], s[100:101]
	v_pk_add_f32 v[162:163], v[162:163], s[100:101]
	v_rcp_f32_e32 v160, v160
	v_rcp_f32_e32 v161, v161
	v_rcp_f32_e32 v162, v162
	v_rcp_f32_e32 v163, v163
	v_pk_mul_f32 v[124:125], v[124:125], v[160:161]
	v_pk_mul_f32 v[126:127], v[126:127], v[162:163]
	v_pk_mul_f32 v[120:121], v[124:125], v[120:121]
	v_pk_mul_f32 v[122:123], v[126:127], v[122:123]
	v_cvt_pk_bf16_f32 v120, v120, v121
	v_cvt_pk_bf16_f32 v121, v122, v123
	v_pk_mul_f32 v[160:161], v[116:117], s[98:99]
	v_pk_mul_f32 v[162:163], v[118:119], s[98:99]
	v_exp_f32_e32 v160, v160
	v_exp_f32_e32 v161, v161
	v_exp_f32_e32 v162, v162
	v_exp_f32_e32 v163, v163
	v_pk_add_f32 v[160:161], v[160:161], s[100:101]
	v_pk_add_f32 v[162:163], v[162:163], s[100:101]
	v_rcp_f32_e32 v160, v160
	v_rcp_f32_e32 v161, v161
	v_rcp_f32_e32 v162, v162
	v_rcp_f32_e32 v163, v163
	v_pk_mul_f32 v[116:117], v[116:117], v[160:161]
	v_pk_mul_f32 v[118:119], v[118:119], v[162:163]
	v_pk_mul_f32 v[112:113], v[116:117], v[112:113]
	v_pk_mul_f32 v[114:115], v[118:119], v[114:115]
	v_cvt_pk_bf16_f32 v122, v112, v113
	v_cvt_pk_bf16_f32 v123, v114, v115
	v_pk_mul_f32 v[160:161], v[108:109], s[98:99]
	v_pk_mul_f32 v[162:163], v[110:111], s[98:99]
	v_exp_f32_e32 v160, v160
	v_exp_f32_e32 v161, v161
	v_exp_f32_e32 v162, v162
	v_exp_f32_e32 v163, v163
	v_pk_add_f32 v[160:161], v[160:161], s[100:101]
	v_pk_add_f32 v[162:163], v[162:163], s[100:101]
	v_rcp_f32_e32 v160, v160
	v_rcp_f32_e32 v161, v161
	v_rcp_f32_e32 v162, v162
	v_rcp_f32_e32 v163, v163
	v_pk_mul_f32 v[108:109], v[108:109], v[160:161]
	v_pk_mul_f32 v[110:111], v[110:111], v[162:163]
	v_pk_mul_f32 v[104:105], v[108:109], v[104:105]
	v_pk_mul_f32 v[106:107], v[110:111], v[106:107]
	v_cvt_pk_bf16_f32 v104, v104, v105
	v_cvt_pk_bf16_f32 v105, v106, v107
	v_pk_mul_f32 v[160:161], v[100:101], s[98:99]
	v_pk_mul_f32 v[162:163], v[102:103], s[98:99]
	v_exp_f32_e32 v160, v160
	v_exp_f32_e32 v161, v161
	v_exp_f32_e32 v162, v162
	v_exp_f32_e32 v163, v163
	v_pk_add_f32 v[160:161], v[160:161], s[100:101]
	v_pk_add_f32 v[162:163], v[162:163], s[100:101]
	v_rcp_f32_e32 v160, v160
	v_rcp_f32_e32 v161, v161
	v_rcp_f32_e32 v162, v162
	v_rcp_f32_e32 v163, v163
	v_pk_mul_f32 v[100:101], v[100:101], v[160:161]
	v_pk_mul_f32 v[102:103], v[102:103], v[162:163]
	v_pk_mul_f32 v[96:97], v[100:101], v[96:97]
	v_pk_mul_f32 v[98:99], v[102:103], v[98:99]
	v_cvt_pk_bf16_f32 v106, v96, v97
	v_cvt_pk_bf16_f32 v107, v98, v99
	v_pk_mul_f32 v[160:161], v[92:93], s[98:99]
	v_pk_mul_f32 v[162:163], v[94:95], s[98:99]
	v_exp_f32_e32 v160, v160
	v_exp_f32_e32 v161, v161
	v_exp_f32_e32 v162, v162
	v_exp_f32_e32 v163, v163
	v_pk_add_f32 v[160:161], v[160:161], s[100:101]
	v_pk_add_f32 v[162:163], v[162:163], s[100:101]
	v_rcp_f32_e32 v160, v160
	v_rcp_f32_e32 v161, v161
	v_rcp_f32_e32 v162, v162
	v_rcp_f32_e32 v163, v163
	v_pk_mul_f32 v[92:93], v[92:93], v[160:161]
	v_pk_mul_f32 v[94:95], v[94:95], v[162:163]
	v_pk_mul_f32 v[88:89], v[92:93], v[88:89]
	v_pk_mul_f32 v[90:91], v[94:95], v[90:91]
	v_cvt_pk_bf16_f32 v88, v88, v89
	v_cvt_pk_bf16_f32 v89, v90, v91
	v_pk_mul_f32 v[160:161], v[84:85], s[98:99]
	v_pk_mul_f32 v[162:163], v[86:87], s[98:99]
	v_exp_f32_e32 v160, v160
	v_exp_f32_e32 v161, v161
	v_exp_f32_e32 v162, v162
	v_exp_f32_e32 v163, v163
	v_pk_add_f32 v[160:161], v[160:161], s[100:101]
	v_pk_add_f32 v[162:163], v[162:163], s[100:101]
	v_rcp_f32_e32 v160, v160
	v_rcp_f32_e32 v161, v161
	v_rcp_f32_e32 v162, v162
	v_rcp_f32_e32 v163, v163
	v_pk_mul_f32 v[84:85], v[84:85], v[160:161]
	v_pk_mul_f32 v[86:87], v[86:87], v[162:163]
	v_pk_mul_f32 v[80:81], v[84:85], v[80:81]
	v_pk_mul_f32 v[82:83], v[86:87], v[82:83]
	v_cvt_pk_bf16_f32 v90, v80, v81
	v_cvt_pk_bf16_f32 v91, v82, v83
	v_pk_mul_f32 v[160:161], v[76:77], s[98:99]
	v_pk_mul_f32 v[162:163], v[78:79], s[98:99]
	v_exp_f32_e32 v160, v160
	v_exp_f32_e32 v161, v161
	v_exp_f32_e32 v162, v162
	v_exp_f32_e32 v163, v163
	v_pk_add_f32 v[160:161], v[160:161], s[100:101]
; __device__ __forceinline__ unsigned cvt_pk_bf16(float lo, float hi) { const f32x2_cv v = {lo, hi}; return __builtin_bit_cast(unsigned, __builtin_convertvector(v, bf16x2_cv)); }
; __device__ __forceinline__ float siluf_(float x) { return x * sigmoidf_(x); }
;     __device__ __forceinline__ void operator()(const f32x4 (&acc)[2][2][4][2], const Unit& u, int wr, int wc, int fr, int fq) const {
;     ...
;             for (int m = 0; m < 4; ++m) { bf16_t* rowp = O + (size_t)(row0 + ai * HALF + m * 16) * ldc + col0;
;                 const f32x4 g0 = acc[ai][0][m][0], g1 = acc[ai][0][m][1], u0 = acc[ai][1][m][0], u1 = acc[ai][1][m][1];
;                 u32x4 w; w.x = cvt_pk_bf16(siluf_(g0[0]) * u0[0], siluf_(g0[1]) * u0[1]); w.y = cvt_pk_bf16(siluf_(g0[2]) * u0[2], siluf_(g0[3]) * u0[3]);
;                 w.z = cvt_pk_bf16(siluf_(g1[0]) * u1[0], siluf_(g1[1]) * u1[1]); w.w = cvt_pk_bf16(siluf_(g1[2]) * u1[2], siluf_(g1[3]) * u1[3]);
;                 __builtin_nontemporal_store(w, (u32x4*)rowp); }
; template <class Epi, class Sched, bool ALIGN_EPI = false, bool SP2 = false>
; __device__ __forceinline__ void gemm_phase(PG8_LAS unsigned char* lds, const Gemm g, const Sched& S, const Epi& E) {
;     ...
;         if (!has_next) break;
	v_pk_add_f32 v[162:163], v[162:163], s[100:101]
	v_rcp_f32_e32 v160, v160
	v_rcp_f32_e32 v161, v161
	v_rcp_f32_e32 v162, v162
	v_rcp_f32_e32 v163, v163
	v_pk_mul_f32 v[76:77], v[76:77], v[160:161]
	v_pk_mul_f32 v[78:79], v[78:79], v[162:163]
	v_pk_mul_f32 v[72:73], v[76:77], v[72:73]
	v_pk_mul_f32 v[74:75], v[78:79], v[74:75]
	v_cvt_pk_bf16_f32 v72, v72, v73
	v_cvt_pk_bf16_f32 v73, v74, v75
	v_pk_mul_f32 v[160:161], v[68:69], s[98:99]
	v_pk_mul_f32 v[162:163], v[70:71], s[98:99]
	v_exp_f32_e32 v160, v160
	v_exp_f32_e32 v161, v161
	v_exp_f32_e32 v162, v162
	v_exp_f32_e32 v163, v163
	v_pk_add_f32 v[160:161], v[160:161], s[100:101]
	v_pk_add_f32 v[162:163], v[162:163], s[100:101]
	v_rcp_f32_e32 v160, v160
	v_rcp_f32_e32 v161, v161
	v_rcp_f32_e32 v162, v162
	v_rcp_f32_e32 v163, v163
	v_pk_mul_f32 v[68:69], v[68:69], v[160:161]
	v_pk_mul_f32 v[70:71], v[70:71], v[162:163]
	v_pk_mul_f32 v[64:65], v[68:69], v[64:65]
	v_pk_mul_f32 v[66:67], v[70:71], v[66:67]
	v_cvt_pk_bf16_f32 v74, v64, v65
	v_cvt_pk_bf16_f32 v75, v66, v67
	v_pk_mul_f32 v[160:161], v[60:61], s[98:99]
	v_pk_mul_f32 v[162:163], v[62:63], s[98:99]
	v_exp_f32_e32 v160, v160
	v_exp_f32_e32 v161, v161
	v_exp_f32_e32 v162, v162
	v_exp_f32_e32 v163, v163
	v_pk_add_f32 v[160:161], v[160:161], s[100:101]
	v_pk_add_f32 v[162:163], v[162:163], s[100:101]
	v_rcp_f32_e32 v160, v160
	v_rcp_f32_e32 v161, v161
	v_rcp_f32_e32 v162, v162
	v_rcp_f32_e32 v163, v163
	v_pk_mul_f32 v[60:61], v[60:61], v[160:161]
	v_pk_mul_f32 v[62:63], v[62:63], v[162:163]
	v_pk_mul_f32 v[56:57], v[60:61], v[56:57]
	v_pk_mul_f32 v[58:59], v[62:63], v[58:59]
	v_cvt_pk_bf16_f32 v56, v56, v57
	v_cvt_pk_bf16_f32 v57, v58, v59
	v_pk_mul_f32 v[160:161], v[52:53], s[98:99]
	v_pk_mul_f32 v[162:163], v[54:55], s[98:99]
	v_exp_f32_e32 v160, v160
	v_exp_f32_e32 v161, v161
	v_exp_f32_e32 v162, v162
	v_exp_f32_e32 v163, v163
	v_pk_add_f32 v[160:161], v[160:161], s[100:101]
	v_pk_add_f32 v[162:163], v[162:163], s[100:101]
	v_rcp_f32_e32 v160, v160
	v_rcp_f32_e32 v161, v161
	v_rcp_f32_e32 v162, v162
	v_rcp_f32_e32 v163, v163
	v_pk_mul_f32 v[52:53], v[52:53], v[160:161]
	v_pk_mul_f32 v[54:55], v[54:55], v[162:163]
	v_pk_mul_f32 v[48:49], v[52:53], v[48:49]
	v_pk_mul_f32 v[50:51], v[54:55], v[50:51]
	v_cvt_pk_bf16_f32 v58, v48, v49
	v_cvt_pk_bf16_f32 v59, v50, v51
	v_pk_mul_f32 v[160:161], v[44:45], s[98:99]
	v_pk_mul_f32 v[162:163], v[46:47], s[98:99]
	v_exp_f32_e32 v160, v160
	v_exp_f32_e32 v161, v161
	v_exp_f32_e32 v162, v162
	v_exp_f32_e32 v163, v163
	v_pk_add_f32 v[160:161], v[160:161], s[100:101]
	v_pk_add_f32 v[162:163], v[162:163], s[100:101]
	v_rcp_f32_e32 v160, v160
	v_rcp_f32_e32 v161, v161
	v_rcp_f32_e32 v162, v162
	v_rcp_f32_e32 v163, v163
	v_pk_mul_f32 v[44:45], v[44:45], v[160:161]
	v_pk_mul_f32 v[46:47], v[46:47], v[162:163]
	v_pk_mul_f32 v[40:41], v[44:45], v[40:41]
	v_pk_mul_f32 v[42:43], v[46:47], v[42:43]
	v_cvt_pk_bf16_f32 v40, v40, v41
	v_cvt_pk_bf16_f32 v41, v42, v43
	v_pk_mul_f32 v[160:161], v[36:37], s[98:99]
	v_pk_mul_f32 v[162:163], v[38:39], s[98:99]
	v_exp_f32_e32 v160, v160
	v_exp_f32_e32 v161, v161
	v_exp_f32_e32 v162, v162
	v_exp_f32_e32 v163, v163
	v_pk_add_f32 v[160:161], v[160:161], s[100:101]
	v_pk_add_f32 v[162:163], v[162:163], s[100:101]
	v_rcp_f32_e32 v160, v160
	v_rcp_f32_e32 v161, v161
	v_rcp_f32_e32 v162, v162
	v_rcp_f32_e32 v163, v163
	v_pk_mul_f32 v[36:37], v[36:37], v[160:161]
	v_pk_mul_f32 v[38:39], v[38:39], v[162:163]
	v_pk_mul_f32 v[32:33], v[36:37], v[32:33]
	v_pk_mul_f32 v[34:35], v[38:39], v[34:35]
	v_cvt_pk_bf16_f32 v42, v32, v33
	v_cvt_pk_bf16_f32 v43, v34, v35
	v_pk_mul_f32 v[160:161], v[28:29], s[98:99]
	v_pk_mul_f32 v[162:163], v[30:31], s[98:99]
	v_exp_f32_e32 v160, v160
	v_exp_f32_e32 v161, v161
	v_exp_f32_e32 v162, v162
	v_exp_f32_e32 v163, v163
	v_pk_add_f32 v[160:161], v[160:161], s[100:101]
	v_pk_add_f32 v[162:163], v[162:163], s[100:101]
	v_rcp_f32_e32 v160, v160
	v_rcp_f32_e32 v161, v161
	v_rcp_f32_e32 v162, v162
	v_rcp_f32_e32 v163, v163
	v_pk_mul_f32 v[28:29], v[28:29], v[160:161]
	v_pk_mul_f32 v[30:31], v[30:31], v[162:163]
	v_pk_mul_f32 v[24:25], v[28:29], v[24:25]
	v_pk_mul_f32 v[26:27], v[30:31], v[26:27]
	v_cvt_pk_bf16_f32 v24, v24, v25
	v_cvt_pk_bf16_f32 v25, v26, v27
	v_pk_mul_f32 v[160:161], v[20:21], s[98:99]
	v_pk_mul_f32 v[162:163], v[22:23], s[98:99]
	v_exp_f32_e32 v160, v160
	v_exp_f32_e32 v161, v161
	v_exp_f32_e32 v162, v162
	v_exp_f32_e32 v163, v163
	v_pk_add_f32 v[160:161], v[160:161], s[100:101]
	v_pk_add_f32 v[162:163], v[162:163], s[100:101]
	v_rcp_f32_e32 v160, v160
	v_rcp_f32_e32 v161, v161
	v_rcp_f32_e32 v162, v162
	v_rcp_f32_e32 v163, v163
	v_pk_mul_f32 v[20:21], v[20:21], v[160:161]
	v_pk_mul_f32 v[22:23], v[22:23], v[162:163]
	v_pk_mul_f32 v[16:17], v[20:21], v[16:17]
	v_pk_mul_f32 v[18:19], v[22:23], v[18:19]
	v_cvt_pk_bf16_f32 v26, v16, v17
	v_cvt_pk_bf16_f32 v27, v18, v19
	v_pk_mul_f32 v[160:161], v[12:13], s[98:99]
	v_pk_mul_f32 v[162:163], v[14:15], s[98:99]
	v_exp_f32_e32 v160, v160
	v_exp_f32_e32 v161, v161
	v_exp_f32_e32 v162, v162
	v_exp_f32_e32 v163, v163
	v_pk_add_f32 v[160:161], v[160:161], s[100:101]
	v_pk_add_f32 v[162:163], v[162:163], s[100:101]
	v_rcp_f32_e32 v160, v160
	v_rcp_f32_e32 v161, v161
	v_rcp_f32_e32 v162, v162
	v_rcp_f32_e32 v163, v163
	v_pk_mul_f32 v[12:13], v[12:13], v[160:161]
	v_pk_mul_f32 v[14:15], v[14:15], v[162:163]
	v_pk_mul_f32 v[8:9], v[12:13], v[8:9]
	v_pk_mul_f32 v[10:11], v[14:15], v[10:11]
	v_cvt_pk_bf16_f32 v8, v8, v9
	v_cvt_pk_bf16_f32 v9, v10, v11
	v_pk_mul_f32 v[160:161], v[4:5], s[98:99]
	v_pk_mul_f32 v[162:163], v[6:7], s[98:99]
	v_exp_f32_e32 v160, v160
	v_exp_f32_e32 v161, v161
	v_exp_f32_e32 v162, v162
	v_exp_f32_e32 v163, v163
	v_pk_add_f32 v[160:161], v[160:161], s[100:101]
	v_pk_add_f32 v[162:163], v[162:163], s[100:101]
	v_rcp_f32_e32 v160, v160
	v_rcp_f32_e32 v161, v161
	v_rcp_f32_e32 v162, v162
	v_rcp_f32_e32 v163, v163
	v_pk_mul_f32 v[4:5], v[4:5], v[160:161]
	v_pk_mul_f32 v[6:7], v[6:7], v[162:163]
	v_pk_mul_f32 v[0:1], v[4:5], v[0:1]
	v_pk_mul_f32 v[2:3], v[6:7], v[2:3]
	v_cvt_pk_bf16_f32 v10, v0, v1
	v_cvt_pk_bf16_f32 v11, v2, v3
	s_andn2_b64 vcc, exec, s[6:7]
	s_mov_b64 s[6:7], -1
	global_store_dwordx4 v[216:217], v[120:123], off nt
	global_store_dwordx4 v[218:219], v[104:107], off nt
	global_store_dwordx4 v[220:221], v[88:91], off nt
	global_store_dwordx4 v[222:223], v[72:75], off nt
	global_store_dwordx4 v[224:225], v[56:59], off nt
	global_store_dwordx4 v[226:227], v[40:43], off nt
	global_store_dwordx4 v[228:229], v[24:27], off nt
	global_store_dwordx4 v[230:231], v[8:11], off nt
	s_cbranch_vccnz .LBB0_962
	s_andn2_b64 vcc, exec, s[2:3]
	s_cbranch_vccnz .LBB0_961
	s_barrier
	s_branch .LBB0_961
